# previous + layer boundary GEMM5>GEMM1 XCD-local with a write-after-read wait on the next group (11 of 14 barriers local)
# speedup vs baseline: 1.0436x; 1.0001x over previous
; __global__ void __launch_bounds__(NWAVES * 64, 2) fwd_kernel(Args args) {
;     ...
;         if (ph + 1 < args.ph_hi || rep + 1 < nrep) { if (args.ph_hi > 1000) grid.sync(); else xcd_barrier(xb); } else __syncthreads();
cvx_decided:
	s_mov_b32 s2, 0x7bf4
	s_bitcmp1_b32 s2, s10
	s_cbranch_scc0 cvx_fullbar
	s_cmp_eq_u32 s101, 1
	s_cbranch_scc0 cvx_fullbar
	v_readlane_b32 s22, v253, 12
	v_readlane_b32 s23, v253, 13
	v_mov_b32_e32 v3, 0
	v_mov_b32_e32 v0, 1
	s_and_b32 s2, s89, 7
	s_lshl_b32 s2, s2, 7
	s_add_i32 s2, s2, 0x3600
	s_add_u32 s22, s22, s2
	s_addc_u32 s23, s23, 0
	global_atomic_add v1, v3, v0, s[22:23] sc0
	s_waitcnt vmcnt(0)
	v_readfirstlane_b32 s2, v1
	s_nop 0
	s_lshr_b32 s3, s2, 5
	s_add_i32 s3, s3, 1
	s_lshl_b32 s3, s3, 5
	s_mov_b32 s2, 0

; __global__ void __launch_bounds__(NWAVES * 64, 2) fwd_kernel(Args args) {
;     ...
;         if (ph + 1 < args.ph_hi || rep + 1 < nrep) { if (args.ph_hi > 1000) grid.sync(); else xcd_barrier(xb); } else __syncthreads();
cvx_arrived:
	s_and_b32 s2, s89, 7
	s_mov_b32 s35, 1
	s_cmp_eq_u32 s10, 8
	s_cbranch_scc1 cvx_w71
	s_cmp_eq_u32 s10, 5
	s_cbranch_scc1 cvx_w45a
	s_cmp_eq_u32 s10, 12
	s_cbranch_scc1 cvx_w45b
	s_cmp_eq_u32 s10, 14
	s_cbranch_scc1 cvx_w67
	s_branch cvx_done

; __global__ void __launch_bounds__(NWAVES * 64, 2) fwd_kernel(Args args) {
;     ...
;         if (ph + 1 < args.ph_hi || rep + 1 < nrep) { if (args.ph_hi > 1000) grid.sync(); else xcd_barrier(xb); } else __syncthreads();
cvx_w45b:
	s_movk_i32 s3, 256

; __global__ void __launch_bounds__(NWAVES * 64, 2) fwd_kernel(Args args) {
;     ...
;         if (ph + 1 < args.ph_hi || rep + 1 < nrep) { if (args.ph_hi > 1000) grid.sync(); else xcd_barrier(xb); } else __syncthreads();
cvx_w71:
	s_cmp_eq_u32 s2, 7
	s_cbranch_scc1 cvx_done
	s_movk_i32 s3, 192
	s_add_u32 s22, s22, 0x80
	s_addc_u32 s23, s23, 0
	s_branch cvx_waitn
cvx_w67:
	s_cmp_gt_u32 s2, 3
	s_cbranch_scc1 cvx_done
	s_movk_i32 s3, 288
	s_mov_b32 s35, 2
	s_lshl_b32 s2, s2, 7
	s_add_u32 s22, s22, s2
	s_addc_u32 s23, s23, 0
